# lora outputs read by the record builder, the hoisted HGRN2 chunk state/gate pieces and the prompt attention query fragments also non-temporal
# baseline (speedup 1.0000x reference)
.LBB0_326:
	s_bfe_u32 s23, s23, 0x10006
	v_bfe_u32 v0, v107, 3, 3
	v_lshl_or_b32 v109, s23, 3, v0
	s_lshl_b32 s14, s26, 6
	v_lshlrev_b32_e32 v106, 3, v108
	v_cmp_gt_u32_e32 vcc, s7, v109
	s_and_b32 s14, s14, 0x1c0
	v_and_b32_e32 v88, 56, v106
	v_cndmask_b32_e32 v0, 0, v109, vcc
	v_or_b32_e32 v14, s14, v88
	v_add_u32_e32 v6, s25, v0
	v_or_b32_e32 v8, s24, v0
	s_waitcnt lgkmcnt(0)
	v_mov_b64_e32 v[0:1], s[4:5]
	v_mad_i64_i32 v[0:1], s[4:5], v6, s83, v[0:1]
	v_lshlrev_b32_e32 v156, 1, v14
	v_lshl_add_u64 v[0:1], v[0:1], 0, v[156:157]
	s_mov_b64 s[4:5], 0x12f01000
	v_lshl_add_u64 v[2:3], v[0:1], 0, s[4:5]
	v_mov_b64_e32 v[4:5], s[2:3]
	s_movk_i32 s2, 0xc00
	s_mov_b32 s4, 0x12f01000
	v_mad_i64_i32 v[4:5], s[2:3], v6, s2, v[4:5]
	v_add_co_u32_e32 v0, vcc, s4, v0
	v_lshl_add_u64 v[4:5], v[4:5], 0, v[156:157]
	s_mov_b64 s[2:3], 0x25600000
	v_addc_co_u32_e32 v1, vcc, 0, v1, vcc
	s_mov_b32 s4, 0x25600000
	v_lshl_add_u64 v[6:7], v[4:5], 0, s[2:3]
	v_cmp_eq_u32_e64 s[2:3], 0, v8
	v_add_co_u32_e32 v4, vcc, s4, v4
	s_nop 0
	v_cndmask_b32_e64 v9, -1, 0, s[2:3]
	v_cndmask_b32_e64 v8, v205, 0, s[2:3]
	v_addc_co_u32_e32 v5, vcc, 0, v5, vcc
	v_lshl_add_u64 v[12:13], v[2:3], 0, v[8:9]
	global_load_dwordx4 v[8:11], v[4:5], off nt
	global_load_dwordx4 v[76:79], v[12:13], off
	global_load_dwordx4 v[32:35], v[12:13], off offset:1024
	global_load_dwordx4 v[36:39], v[2:3], off offset:1024
	global_load_dwordx4 v[24:27], v[2:3], off offset:2048
	s_load_dwordx2 s[4:5], s[18:19], 0xb0
	v_lshlrev_b32_e32 v156, 2, v14
	global_load_dwordx4 v[80:83], v[0:1], off
	global_load_dwordx4 v[28:31], v[12:13], off offset:2048
	global_load_dwordx4 v[72:75], v[6:7], off offset:1024 nt
	s_nop 0
	global_load_dwordx4 v[0:3], v[6:7], off offset:2048 nt
	s_waitcnt lgkmcnt(0)
	global_load_dwordx4 v[52:55], v156, s[4:5] offset:16
	global_load_dwordx4 v[56:59], v156, s[4:5]
	global_load_dwordx4 v[40:43], v156, s[4:5] offset:2064
	global_load_dwordx4 v[48:51], v156, s[4:5] offset:2048
	v_lshl_add_u64 v[4:5], s[4:5], 0, v[156:157]
	v_lshl_add_u64 v[6:7], v[4:5], 0, s[46:47]
	v_add_co_u32_e32 v4, vcc, 0x1000, v4
	v_cmp_le_u32_e64 s[4:5], s7, v109
	s_nop 0
	v_addc_co_u32_e32 v5, vcc, 0, v5, vcc
	global_load_dwordx4 v[12:15], v[4:5], off
	s_nop 0
	global_load_dwordx4 v[4:7], v[6:7], off offset:16
	s_and_b64 s[14:15], s[12:13], s[2:3]
	v_mov_b32_e32 v60, 0
	v_mov_b32_e32 v61, 0
	v_mov_b32_e32 v62, 0
	v_mov_b32_e32 v63, 0
	v_mov_b32_e32 v64, 0
	v_mov_b32_e32 v65, 0
	v_mov_b32_e32 v66, 0
	v_mov_b32_e32 v67, 0
	v_mov_b32_e32 v68, 0
	v_mov_b32_e32 v69, 0
	v_mov_b32_e32 v70, 0
	v_mov_b32_e32 v71, 0
	v_mov_b32_e32 v44, 0
	v_mov_b32_e32 v45, 0
	v_mov_b32_e32 v46, 0
	v_mov_b32_e32 v47, 0
	v_mov_b32_e32 v20, 0
	v_mov_b32_e32 v21, 0
	v_mov_b32_e32 v22, 0
	v_mov_b32_e32 v23, 0
	v_mov_b32_e32 v16, 0
	v_mov_b32_e32 v17, 0
	v_mov_b32_e32 v18, 0
	v_mov_b32_e32 v19, 0
	s_and_saveexec_b64 s[12:13], s[14:15]
	s_cbranch_execz .LBB0_328
	s_load_dwordx2 s[14:15], s[18:19], 0x30
	s_mul_hi_i32 s7, s1, 0x1c00
	s_mulk_i32 s1, 0x1c00
	s_waitcnt lgkmcnt(0)
	s_add_u32 s14, s14, s1
	s_addc_u32 s15, s15, s7
	v_lshl_add_u64 v[16:17], s[14:15], 0, v[156:157]
	global_load_dwordx4 v[60:63], v156, s[14:15]
	global_load_dwordx4 v[64:67], v156, s[14:15] offset:16
	global_load_dwordx4 v[68:71], v156, s[14:15] offset:2048
	global_load_dwordx4 v[44:47], v156, s[14:15] offset:2064
	v_lshl_add_u64 v[18:19], v[16:17], 0, s[46:47]
	v_add_co_u32_e32 v16, vcc, 0x1000, v16
	s_nop 1
	v_addc_co_u32_e32 v17, vcc, 0, v17, vcc
	global_load_dwordx4 v[20:23], v[16:17], off
	s_nop 0
	global_load_dwordx4 v[16:19], v[18:19], off offset:16

.LBB0_494:
	v_add_u32_e32 v174, s0, v156
	ds_read_b128 v[144:147], v174
	v_add_u32_e32 v148, 0x10800, v174
	v_add_u32_e32 v149, 0x14a00, v174
	v_add_u32_e32 v151, 0x1ce00, v174
	v_add_u32_e32 v150, 0x18c00, v174
	s_min_u32 s5, s1, 5
	s_lshl_b32 s30, s5, 6
	s_add_i32 s1, s1, 1
	s_add_i32 s0, s0, 64
	s_waitcnt lgkmcnt(0)
	v_mfma_f32_32x32x16_bf16 v[112:127], v[144:147], v[140:143], v[112:127]
	ds_read_b128 v[144:147], v174 offset:16896
	s_cmpk_eq_i32 s0, 0x200
	ds_read_b128 v[170:173], v151
	s_waitcnt lgkmcnt(1)
	v_mfma_f32_32x32x16_bf16 v[96:111], v[144:147], v[140:143], v[96:111]
	ds_read_b128 v[144:147], v174 offset:33792
	s_waitcnt lgkmcnt(0)
	v_mfma_f32_32x32x16_bf16 v[80:95], v[144:147], v[140:143], v[80:95]
	ds_read_b128 v[144:147], v174 offset:50688
	s_waitcnt lgkmcnt(0)
	v_mfma_f32_32x32x16_bf16 v[64:79], v[144:147], v[140:143], v[64:79]
	ds_read_b128 v[144:147], v148
	s_waitcnt lgkmcnt(0)
	v_mfma_f32_32x32x16_bf16 v[48:63], v[144:147], v[140:143], v[48:63]
	ds_read_b128 v[144:147], v149
	v_lshl_add_u64 v[148:149], v[162:163], 0, s[30:31]
	s_waitcnt lgkmcnt(0)
	v_mfma_f32_32x32x16_bf16 v[32:47], v[144:147], v[140:143], v[32:47]
	ds_read_b128 v[144:147], v150
	s_waitcnt lgkmcnt(0)
	v_mfma_f32_32x32x16_bf16 v[16:31], v[144:147], v[140:143], v[16:31]
	global_load_dwordx4 v[144:147], v[148:149], off offset:128 nt
	s_nop 0
	global_load_dwordx4 v[148:151], v[148:149], off offset:160 nt
	v_mfma_f32_32x32x16_bf16 v[0:15], v[170:173], v[140:143], v[0:15]
	ds_read_b128 v[140:143], v174 offset:32
	v_add_u32_e32 v170, 0x10820, v174
	v_add_u32_e32 v171, 0x14a20, v174
	v_add_u32_e32 v172, 0x18c20, v174
	v_add_u32_e32 v173, 0x1ce20, v174
	s_waitcnt lgkmcnt(0)
	v_mfma_f32_32x32x16_bf16 v[112:127], v[140:143], v[136:139], v[112:127]
	ds_read_b128 v[140:143], v174 offset:16928
	s_waitcnt lgkmcnt(0)
	v_mfma_f32_32x32x16_bf16 v[96:111], v[140:143], v[136:139], v[96:111]
	ds_read_b128 v[140:143], v174 offset:33824
	s_waitcnt lgkmcnt(0)
	v_mfma_f32_32x32x16_bf16 v[80:95], v[140:143], v[136:139], v[80:95]
	ds_read_b128 v[140:143], v174 offset:50720
	s_waitcnt lgkmcnt(0)
	v_mfma_f32_32x32x16_bf16 v[64:79], v[140:143], v[136:139], v[64:79]
	ds_read_b128 v[140:143], v170
	s_waitcnt lgkmcnt(0)
	v_mfma_f32_32x32x16_bf16 v[48:63], v[140:143], v[136:139], v[48:63]
	ds_read_b128 v[140:143], v171
	s_waitcnt lgkmcnt(0)
	v_mfma_f32_32x32x16_bf16 v[32:47], v[140:143], v[136:139], v[32:47]
	ds_read_b128 v[140:143], v172
	s_waitcnt lgkmcnt(0)
	v_mfma_f32_32x32x16_bf16 v[16:31], v[140:143], v[136:139], v[16:31]
	ds_read_b128 v[140:143], v173
	s_waitcnt lgkmcnt(0)
	v_mfma_f32_32x32x16_bf16 v[0:15], v[140:143], v[136:139], v[0:15]
	v_mov_b64_e32 v[142:143], v[130:131]
	v_mov_b64_e32 v[138:139], v[134:135]
	v_mov_b64_e32 v[140:141], v[128:129]
	v_mov_b64_e32 v[136:137], v[132:133]
	s_waitcnt vmcnt(1)
	v_mov_b64_e32 v[128:129], v[144:145]
	s_waitcnt vmcnt(0)
	v_mov_b64_e32 v[132:133], v[148:149]
	v_mov_b64_e32 v[130:131], v[146:147]
	v_mov_b64_e32 v[134:135], v[150:151]
	s_cbranch_scc0 .LBB0_494
	v_max3_f32 v128, v112, s51, v113
	v_max3_f32 v128, v128, v114, v115
	v_max3_f32 v128, v128, v116, v117
	v_max3_f32 v128, v128, v118, v119
	v_max3_f32 v128, v128, v120, v121
	v_max3_f32 v128, v128, v122, v123
	v_max3_f32 v128, v128, v124, v125
	v_max3_f32 v128, v128, v126, v127
	v_max3_f32 v128, v128, v96, v97
	v_max3_f32 v128, v128, v98, v99
	v_max3_f32 v128, v128, v100, v101
	v_max3_f32 v128, v128, v102, v103
	v_max3_f32 v128, v128, v104, v105
	v_max3_f32 v128, v128, v106, v107
	v_max3_f32 v128, v128, v108, v109
	v_max3_f32 v128, v128, v110, v111
	v_max3_f32 v128, v128, v80, v81
	v_max3_f32 v128, v128, v82, v83
	v_max3_f32 v128, v128, v84, v85
	v_max3_f32 v128, v128, v86, v87
	v_max3_f32 v128, v128, v88, v89
	v_max3_f32 v128, v128, v90, v91
	v_max3_f32 v128, v128, v92, v93
	v_max3_f32 v128, v128, v94, v95
	v_max3_f32 v128, v128, v64, v65
	v_max3_f32 v128, v128, v66, v67
	v_max3_f32 v128, v128, v68, v69
	v_max3_f32 v128, v128, v70, v71
	v_max3_f32 v128, v128, v72, v73
	v_max3_f32 v128, v128, v74, v75
	v_max3_f32 v128, v128, v76, v77
	v_max3_f32 v128, v128, v78, v79
	v_max3_f32 v128, v128, v48, v49
	v_max3_f32 v128, v128, v50, v51
	v_max3_f32 v128, v128, v52, v53
	v_max3_f32 v128, v128, v54, v55
	v_max3_f32 v128, v128, v56, v57
	v_max3_f32 v128, v128, v58, v59
	v_max3_f32 v128, v128, v60, v61
	v_max3_f32 v128, v128, v62, v63
	v_max3_f32 v128, v128, v32, v33
	v_max3_f32 v128, v128, v34, v35
	v_max3_f32 v128, v128, v36, v37
	v_max3_f32 v128, v128, v38, v39
	v_max3_f32 v128, v128, v40, v41
	v_max3_f32 v128, v128, v42, v43
	v_max3_f32 v128, v128, v44, v45
	v_max3_f32 v128, v128, v46, v47
	v_max3_f32 v128, v128, v16, v17
	v_max3_f32 v128, v128, v18, v19
	v_max3_f32 v128, v128, v20, v21
	v_max3_f32 v128, v128, v22, v23
	v_max3_f32 v128, v128, v24, v25
	v_max3_f32 v128, v128, v26, v27
	v_max3_f32 v128, v128, v28, v29
	v_max3_f32 v128, v128, v30, v31
	v_max3_f32 v128, v128, v0, v1
	v_max3_f32 v128, v128, v2, v3
	v_max3_f32 v128, v128, v4, v5
	v_max3_f32 v128, v128, v6, v7
	v_max3_f32 v128, v128, v8, v9
	v_max3_f32 v128, v128, v10, v11
	v_max3_f32 v128, v128, v12, v13
	v_and_b32_e32 v130, 64, v208
	v_max3_f32 v129, v128, v14, v15
	v_xor_b32_e32 v128, 32, v208
	v_add_u32_e32 v130, 64, v130
	v_cmp_lt_i32_e32 vcc, v128, v130
	s_barrier
	s_nop 0
	v_cndmask_b32_e32 v128, v208, v128, vcc
	v_lshlrev_b32_e32 v128, 2, v128
	ds_bpermute_b32 v130, v128, v129
	s_waitcnt lgkmcnt(0)
	s_add_u32 s6, s6, s18
	s_addc_u32 s7, s7, s19
	v_lshlrev_b32_e32 v156, 1, v160
	v_max_f32_e32 v130, v130, v130
	v_max_f32_e32 v129, v129, v130
	v_sub_f32_e32 v112, v112, v129
	v_mul_f32_e32 v112, 0x3db8aa3b, v112
	v_exp_f32_e32 v130, v112
	v_sub_f32_e32 v112, v113, v129
	v_mul_f32_e32 v112, 0x3db8aa3b, v112
	v_exp_f32_e32 v131, v112
	v_sub_f32_e32 v112, v114, v129
	v_mul_f32_e32 v112, 0x3db8aa3b, v112
	v_exp_f32_e32 v132, v112
	v_sub_f32_e32 v112, v115, v129
	v_mul_f32_e32 v112, 0x3db8aa3b, v112
	v_exp_f32_e32 v133, v112
	v_sub_f32_e32 v112, v116, v129
	v_mul_f32_e32 v112, 0x3db8aa3b, v112
	v_exp_f32_e32 v134, v112
	v_sub_f32_e32 v112, v117, v129
	v_mul_f32_e32 v112, 0x3db8aa3b, v112
	v_exp_f32_e32 v135, v112
	v_sub_f32_e32 v112, v118, v129
	v_mul_f32_e32 v112, 0x3db8aa3b, v112
	v_exp_f32_e32 v136, v112
	v_sub_f32_e32 v112, v119, v129
	v_mul_f32_e32 v112, 0x3db8aa3b, v112
	v_exp_f32_e32 v137, v112
	v_sub_f32_e32 v112, v120, v129
	v_mul_f32_e32 v112, 0x3db8aa3b, v112
	v_exp_f32_e32 v120, v112
	v_sub_f32_e32 v112, v121, v129
	v_mul_f32_e32 v112, 0x3db8aa3b, v112
	v_exp_f32_e32 v121, v112
	v_sub_f32_e32 v112, v122, v129
	v_mul_f32_e32 v112, 0x3db8aa3b, v112
	v_exp_f32_e32 v122, v112
	v_sub_f32_e32 v112, v123, v129
	v_mul_f32_e32 v112, 0x3db8aa3b, v112
	v_exp_f32_e32 v123, v112
	v_sub_f32_e32 v112, v124, v129
	v_mul_f32_e32 v112, 0x3db8aa3b, v112
	v_exp_f32_e32 v124, v112
	v_sub_f32_e32 v112, v125, v129
	v_mul_f32_e32 v112, 0x3db8aa3b, v112
	v_exp_f32_e32 v125, v112
	v_sub_f32_e32 v112, v126, v129
	v_mul_f32_e32 v112, 0x3db8aa3b, v112
	v_exp_f32_e32 v126, v112
	v_sub_f32_e32 v112, v127, v129
	v_mul_f32_e32 v112, 0x3db8aa3b, v112
	v_exp_f32_e32 v127, v112
	v_cvt_pk_bf16_f32 v112, v130, v131
	v_add_f32_e32 v130, 0, v130
	v_add_f32_e32 v130, v131, v130
	v_add_f32_e32 v130, v132, v130
	v_add_f32_e32 v130, v133, v130
	v_add_f32_e32 v130, v134, v130
	v_add_f32_e32 v130, v135, v130
	v_add_f32_e32 v130, v136, v130
	v_add_f32_e32 v130, v137, v130
	v_sub_f32_e32 v96, v96, v129
	v_cvt_pk_bf16_f32 v113, v132, v133
	v_cvt_pk_bf16_f32 v114, v134, v135
	v_cvt_pk_bf16_f32 v115, v136, v137
	v_cvt_pk_bf16_f32 v116, v120, v121
	v_add_f32_e32 v120, v120, v130
	v_mul_f32_e32 v96, 0x3db8aa3b, v96
	v_add_f32_e32 v120, v121, v120
	v_exp_f32_e32 v121, v96
	v_sub_f32_e32 v96, v97, v129
	v_mul_f32_e32 v96, 0x3db8aa3b, v96
	v_cvt_pk_bf16_f32 v117, v122, v123
	v_add_f32_e32 v120, v122, v120
	v_exp_f32_e32 v122, v96
	v_sub_f32_e32 v96, v98, v129
	v_mul_f32_e32 v96, 0x3db8aa3b, v96
	v_add_f32_e32 v120, v123, v120
	v_exp_f32_e32 v123, v96
	v_sub_f32_e32 v96, v99, v129
	v_mul_f32_e32 v96, 0x3db8aa3b, v96
	v_cvt_pk_bf16_f32 v118, v124, v125
	v_add_f32_e32 v120, v124, v120
	v_exp_f32_e32 v124, v96
	v_sub_f32_e32 v96, v100, v129
	v_mul_f32_e32 v96, 0x3db8aa3b, v96
	v_add_f32_e32 v120, v125, v120
	v_exp_f32_e32 v125, v96
	v_sub_f32_e32 v96, v101, v129
	v_mul_f32_e32 v96, 0x3db8aa3b, v96
	v_cvt_pk_bf16_f32 v119, v126, v127
	v_add_f32_e32 v120, v126, v120
	v_exp_f32_e32 v126, v96
	v_sub_f32_e32 v96, v102, v129
	v_mul_f32_e32 v96, 0x3db8aa3b, v96
	v_add_f32_e32 v120, v127, v120
	v_exp_f32_e32 v127, v96
	v_sub_f32_e32 v96, v103, v129
	v_mul_f32_e32 v96, 0x3db8aa3b, v96
	v_exp_f32_e32 v130, v96
	v_sub_f32_e32 v96, v104, v129
	v_mul_f32_e32 v96, 0x3db8aa3b, v96
	v_exp_f32_e32 v104, v96
	v_sub_f32_e32 v96, v105, v129
	v_mul_f32_e32 v96, 0x3db8aa3b, v96
	v_exp_f32_e32 v105, v96
	v_sub_f32_e32 v96, v106, v129
	v_mul_f32_e32 v96, 0x3db8aa3b, v96
	v_exp_f32_e32 v106, v96
	v_sub_f32_e32 v96, v107, v129
	v_mul_f32_e32 v96, 0x3db8aa3b, v96
	v_exp_f32_e32 v107, v96
	v_sub_f32_e32 v96, v108, v129
	v_add_f32_e32 v120, v121, v120
	v_mul_f32_e32 v96, 0x3db8aa3b, v96
	v_add_f32_e32 v120, v122, v120
	v_exp_f32_e32 v108, v96
	v_sub_f32_e32 v96, v109, v129
	v_add_f32_e32 v120, v123, v120
	v_mul_f32_e32 v96, 0x3db8aa3b, v96
	v_add_f32_e32 v120, v124, v120
	v_exp_f32_e32 v109, v96
	v_sub_f32_e32 v96, v110, v129
	v_add_f32_e32 v120, v125, v120
	v_mul_f32_e32 v96, 0x3db8aa3b, v96
	v_add_f32_e32 v120, v126, v120
	v_exp_f32_e32 v110, v96
	v_sub_f32_e32 v96, v111, v129
	v_add_f32_e32 v120, v127, v120
	v_mul_f32_e32 v96, 0x3db8aa3b, v96
	v_add_f32_e32 v120, v130, v120
	v_sub_f32_e32 v80, v80, v129
	v_exp_f32_e32 v111, v96
	v_cvt_pk_bf16_f32 v96, v121, v122
	v_cvt_pk_bf16_f32 v97, v123, v124
	v_cvt_pk_bf16_f32 v98, v125, v126
	v_cvt_pk_bf16_f32 v99, v127, v130
	v_cvt_pk_bf16_f32 v100, v104, v105
	v_add_f32_e32 v104, v104, v120
	v_mul_f32_e32 v80, 0x3db8aa3b, v80
	v_add_f32_e32 v104, v105, v104
	v_exp_f32_e32 v105, v80
	v_sub_f32_e32 v80, v81, v129
	v_mul_f32_e32 v80, 0x3db8aa3b, v80
	v_cvt_pk_bf16_f32 v101, v106, v107
	v_add_f32_e32 v104, v106, v104
	v_exp_f32_e32 v106, v80
	v_sub_f32_e32 v80, v82, v129
	v_mul_f32_e32 v80, 0x3db8aa3b, v80
	v_add_f32_e32 v104, v107, v104
	v_exp_f32_e32 v107, v80
	v_sub_f32_e32 v80, v83, v129
	v_mul_f32_e32 v80, 0x3db8aa3b, v80
	v_cvt_pk_bf16_f32 v102, v108, v109
	v_add_f32_e32 v104, v108, v104
	v_exp_f32_e32 v108, v80
	v_sub_f32_e32 v80, v84, v129
	v_mul_f32_e32 v80, 0x3db8aa3b, v80
	v_add_f32_e32 v104, v109, v104
	v_exp_f32_e32 v109, v80
	v_sub_f32_e32 v80, v85, v129
	v_mul_f32_e32 v80, 0x3db8aa3b, v80
	v_cvt_pk_bf16_f32 v103, v110, v111
	v_add_f32_e32 v104, v110, v104
	v_exp_f32_e32 v110, v80
	v_sub_f32_e32 v80, v86, v129
	v_mul_f32_e32 v80, 0x3db8aa3b, v80
	v_add_f32_e32 v104, v111, v104
	v_exp_f32_e32 v111, v80
	v_sub_f32_e32 v80, v87, v129
	v_mul_f32_e32 v80, 0x3db8aa3b, v80
	v_exp_f32_e32 v120, v80
	v_sub_f32_e32 v80, v88, v129
	v_mul_f32_e32 v80, 0x3db8aa3b, v80
	v_exp_f32_e32 v88, v80
	v_sub_f32_e32 v80, v89, v129
	v_mul_f32_e32 v80, 0x3db8aa3b, v80
	v_exp_f32_e32 v89, v80
	v_sub_f32_e32 v80, v90, v129
	v_mul_f32_e32 v80, 0x3db8aa3b, v80
	v_exp_f32_e32 v90, v80
	v_sub_f32_e32 v80, v91, v129
	v_mul_f32_e32 v80, 0x3db8aa3b, v80
	v_exp_f32_e32 v91, v80
	v_sub_f32_e32 v80, v92, v129
	v_add_f32_e32 v104, v105, v104
	v_mul_f32_e32 v80, 0x3db8aa3b, v80
	v_add_f32_e32 v104, v106, v104
	v_exp_f32_e32 v92, v80
	v_sub_f32_e32 v80, v93, v129
	v_add_f32_e32 v104, v107, v104
	v_mul_f32_e32 v80, 0x3db8aa3b, v80
	v_add_f32_e32 v104, v108, v104
	v_exp_f32_e32 v93, v80
	v_sub_f32_e32 v80, v94, v129
	v_add_f32_e32 v104, v109, v104
	v_mul_f32_e32 v80, 0x3db8aa3b, v80
	v_add_f32_e32 v104, v110, v104
	v_exp_f32_e32 v94, v80
	v_sub_f32_e32 v80, v95, v129
	v_add_f32_e32 v104, v111, v104
	v_mul_f32_e32 v80, 0x3db8aa3b, v80
	v_add_f32_e32 v104, v120, v104
	v_sub_f32_e32 v64, v64, v129
	v_exp_f32_e32 v95, v80
	v_cvt_pk_bf16_f32 v80, v105, v106
	v_cvt_pk_bf16_f32 v81, v107, v108
	v_cvt_pk_bf16_f32 v82, v109, v110
	v_cvt_pk_bf16_f32 v83, v111, v120
	v_cvt_pk_bf16_f32 v84, v88, v89
	v_add_f32_e32 v88, v88, v104
	v_mul_f32_e32 v64, 0x3db8aa3b, v64
	v_add_f32_e32 v88, v89, v88
	v_exp_f32_e32 v89, v64
	v_sub_f32_e32 v64, v65, v129
	v_mul_f32_e32 v64, 0x3db8aa3b, v64
	v_cvt_pk_bf16_f32 v85, v90, v91
	v_add_f32_e32 v88, v90, v88
	v_exp_f32_e32 v90, v64
	v_sub_f32_e32 v64, v66, v129
	v_mul_f32_e32 v64, 0x3db8aa3b, v64
	v_add_f32_e32 v88, v91, v88
	v_exp_f32_e32 v91, v64
	v_sub_f32_e32 v64, v67, v129
	v_mul_f32_e32 v64, 0x3db8aa3b, v64
	v_cvt_pk_bf16_f32 v86, v92, v93
	v_add_f32_e32 v88, v92, v88
	v_exp_f32_e32 v92, v64
	v_sub_f32_e32 v64, v68, v129
	v_mul_f32_e32 v64, 0x3db8aa3b, v64
	v_add_f32_e32 v88, v93, v88
	v_exp_f32_e32 v93, v64
	v_sub_f32_e32 v64, v69, v129
	v_mul_f32_e32 v64, 0x3db8aa3b, v64
	v_cvt_pk_bf16_f32 v87, v94, v95
	v_add_f32_e32 v88, v94, v88
	v_exp_f32_e32 v94, v64
	v_sub_f32_e32 v64, v70, v129
	v_mul_f32_e32 v64, 0x3db8aa3b, v64
	v_add_f32_e32 v88, v95, v88
	v_exp_f32_e32 v95, v64
	v_sub_f32_e32 v64, v71, v129
	v_mul_f32_e32 v64, 0x3db8aa3b, v64
	v_exp_f32_e32 v104, v64
	v_sub_f32_e32 v64, v72, v129
	v_mul_f32_e32 v64, 0x3db8aa3b, v64
	v_exp_f32_e32 v72, v64
	v_sub_f32_e32 v64, v73, v129
	v_mul_f32_e32 v64, 0x3db8aa3b, v64
	v_exp_f32_e32 v73, v64
	v_sub_f32_e32 v64, v74, v129
	v_mul_f32_e32 v64, 0x3db8aa3b, v64
	v_exp_f32_e32 v74, v64
	v_sub_f32_e32 v64, v75, v129
	v_mul_f32_e32 v64, 0x3db8aa3b, v64
	v_exp_f32_e32 v75, v64
	v_sub_f32_e32 v64, v76, v129
	v_add_f32_e32 v88, v89, v88
	v_mul_f32_e32 v64, 0x3db8aa3b, v64
	v_add_f32_e32 v88, v90, v88
	v_exp_f32_e32 v76, v64
	v_sub_f32_e32 v64, v77, v129
	v_add_f32_e32 v88, v91, v88
	v_mul_f32_e32 v64, 0x3db8aa3b, v64
	v_add_f32_e32 v88, v92, v88
	v_exp_f32_e32 v77, v64
	v_sub_f32_e32 v64, v78, v129
	v_add_f32_e32 v88, v93, v88
	v_mul_f32_e32 v64, 0x3db8aa3b, v64
	v_add_f32_e32 v88, v94, v88
	v_exp_f32_e32 v78, v64
	v_sub_f32_e32 v64, v79, v129
	v_add_f32_e32 v88, v95, v88
	v_mul_f32_e32 v64, 0x3db8aa3b, v64
	v_add_f32_e32 v88, v104, v88
	v_exp_f32_e32 v79, v64
	v_cvt_pk_bf16_f32 v64, v89, v90
	v_cvt_pk_bf16_f32 v65, v91, v92
	v_cvt_pk_bf16_f32 v66, v93, v94
	v_cvt_pk_bf16_f32 v67, v95, v104
	v_cvt_pk_bf16_f32 v68, v72, v73
	v_add_f32_e32 v72, v72, v88
	v_add_f32_e32 v72, v73, v72
	v_add_f32_e32 v72, v74, v72
	v_sub_f32_e32 v48, v48, v129
	v_add_f32_e32 v72, v75, v72
	v_mul_f32_e32 v48, 0x3db8aa3b, v48
	v_sub_f32_e32 v49, v49, v129
	v_add_f32_e32 v72, v76, v72
	v_exp_f32_e32 v48, v48
	v_mul_f32_e32 v49, 0x3db8aa3b, v49
	v_sub_f32_e32 v50, v50, v129
	v_add_f32_e32 v72, v77, v72
	v_exp_f32_e32 v49, v49
	v_mul_f32_e32 v50, 0x3db8aa3b, v50
	v_sub_f32_e32 v51, v51, v129
	v_add_f32_e32 v72, v78, v72
	v_exp_f32_e32 v50, v50
	v_mul_f32_e32 v51, 0x3db8aa3b, v51
	v_sub_f32_e32 v52, v52, v129
	v_add_f32_e32 v88, v79, v72
	v_exp_f32_e32 v51, v51
	v_mul_f32_e32 v52, 0x3db8aa3b, v52
	v_sub_f32_e32 v53, v53, v129
	v_cvt_pk_bf16_f32 v69, v74, v75
	v_cvt_pk_bf16_f32 v70, v76, v77
	v_cvt_pk_bf16_f32 v71, v78, v79
	v_exp_f32_e32 v52, v52
	v_mul_f32_e32 v53, 0x3db8aa3b, v53
	v_sub_f32_e32 v54, v54, v129
	v_cvt_pk_bf16_f32 v72, v48, v49
	v_add_f32_e32 v48, v48, v88
	v_exp_f32_e32 v53, v53
	v_mul_f32_e32 v54, 0x3db8aa3b, v54
	v_sub_f32_e32 v55, v55, v129
	v_add_f32_e32 v48, v49, v48
	v_exp_f32_e32 v54, v54
	v_mul_f32_e32 v55, 0x3db8aa3b, v55
	v_sub_f32_e32 v56, v56, v129
	v_add_f32_e32 v48, v50, v48
	v_exp_f32_e32 v55, v55
	v_mul_f32_e32 v56, 0x3db8aa3b, v56
	v_sub_f32_e32 v57, v57, v129
	v_add_f32_e32 v48, v51, v48
	v_exp_f32_e32 v56, v56
	v_mul_f32_e32 v57, 0x3db8aa3b, v57
	v_sub_f32_e32 v58, v58, v129
	v_add_f32_e32 v48, v52, v48
	v_exp_f32_e32 v57, v57
	v_mul_f32_e32 v58, 0x3db8aa3b, v58
	v_sub_f32_e32 v59, v59, v129
	v_add_f32_e32 v48, v53, v48
	v_exp_f32_e32 v58, v58
	v_mul_f32_e32 v59, 0x3db8aa3b, v59
	v_sub_f32_e32 v60, v60, v129
	v_add_f32_e32 v48, v54, v48
	v_exp_f32_e32 v59, v59
	v_mul_f32_e32 v60, 0x3db8aa3b, v60
	v_sub_f32_e32 v61, v61, v129
	v_add_f32_e32 v48, v55, v48
	v_exp_f32_e32 v60, v60
	v_mul_f32_e32 v61, 0x3db8aa3b, v61
	v_sub_f32_e32 v62, v62, v129
	v_add_f32_e32 v48, v56, v48
	v_exp_f32_e32 v61, v61
	v_mul_f32_e32 v62, 0x3db8aa3b, v62
	v_sub_f32_e32 v63, v63, v129
	v_add_f32_e32 v48, v57, v48
	v_exp_f32_e32 v62, v62
	v_mul_f32_e32 v63, 0x3db8aa3b, v63
	v_add_f32_e32 v48, v58, v48
	v_sub_f32_e32 v32, v32, v129
	v_exp_f32_e32 v63, v63
	v_add_f32_e32 v48, v59, v48
	v_mul_f32_e32 v32, 0x3db8aa3b, v32
	v_sub_f32_e32 v33, v33, v129
	v_add_f32_e32 v48, v60, v48
	v_exp_f32_e32 v32, v32
	v_mul_f32_e32 v33, 0x3db8aa3b, v33
	v_sub_f32_e32 v34, v34, v129
	v_add_f32_e32 v48, v61, v48
	v_exp_f32_e32 v33, v33
	v_mul_f32_e32 v34, 0x3db8aa3b, v34
	v_sub_f32_e32 v35, v35, v129
	v_add_f32_e32 v48, v62, v48
	v_exp_f32_e32 v34, v34
	v_mul_f32_e32 v35, 0x3db8aa3b, v35
	v_sub_f32_e32 v36, v36, v129
	v_add_f32_e32 v48, v63, v48
	v_exp_f32_e32 v35, v35
	v_mul_f32_e32 v36, 0x3db8aa3b, v36
	v_sub_f32_e32 v37, v37, v129
	v_cvt_pk_bf16_f32 v73, v50, v51
	v_cvt_pk_bf16_f32 v74, v52, v53
	v_cvt_pk_bf16_f32 v75, v54, v55
	v_cvt_pk_bf16_f32 v76, v56, v57
	v_cvt_pk_bf16_f32 v77, v58, v59
	v_cvt_pk_bf16_f32 v78, v60, v61
	v_cvt_pk_bf16_f32 v79, v62, v63
	v_exp_f32_e32 v36, v36
	v_mul_f32_e32 v37, 0x3db8aa3b, v37
	v_sub_f32_e32 v38, v38, v129
	v_cvt_pk_bf16_f32 v88, v32, v33
	v_add_f32_e32 v32, v32, v48
	v_exp_f32_e32 v37, v37
	v_mul_f32_e32 v38, 0x3db8aa3b, v38
	v_sub_f32_e32 v39, v39, v129
	v_add_f32_e32 v32, v33, v32
	v_exp_f32_e32 v38, v38
	v_mul_f32_e32 v39, 0x3db8aa3b, v39
	v_sub_f32_e32 v40, v40, v129
	v_add_f32_e32 v32, v34, v32
	v_exp_f32_e32 v39, v39
	v_mul_f32_e32 v40, 0x3db8aa3b, v40
	v_sub_f32_e32 v41, v41, v129
	v_add_f32_e32 v32, v35, v32
	v_exp_f32_e32 v40, v40
	v_mul_f32_e32 v41, 0x3db8aa3b, v41
	v_sub_f32_e32 v42, v42, v129
	v_add_f32_e32 v32, v36, v32
	v_exp_f32_e32 v41, v41
	v_mul_f32_e32 v42, 0x3db8aa3b, v42
	v_sub_f32_e32 v43, v43, v129
	v_add_f32_e32 v32, v37, v32
	v_exp_f32_e32 v42, v42
	v_mul_f32_e32 v43, 0x3db8aa3b, v43
	v_sub_f32_e32 v44, v44, v129
	v_add_f32_e32 v32, v38, v32
	v_exp_f32_e32 v43, v43
	v_mul_f32_e32 v44, 0x3db8aa3b, v44
	v_sub_f32_e32 v45, v45, v129
	v_add_f32_e32 v32, v39, v32
	v_exp_f32_e32 v44, v44
	v_mul_f32_e32 v45, 0x3db8aa3b, v45
	v_sub_f32_e32 v46, v46, v129
	v_add_f32_e32 v32, v40, v32
	v_exp_f32_e32 v45, v45
	v_mul_f32_e32 v46, 0x3db8aa3b, v46
	v_sub_f32_e32 v47, v47, v129
	v_add_f32_e32 v32, v41, v32
	v_exp_f32_e32 v46, v46
	v_mul_f32_e32 v47, 0x3db8aa3b, v47
	v_add_f32_e32 v32, v42, v32
	v_sub_f32_e32 v16, v16, v129
	v_exp_f32_e32 v47, v47
	v_add_f32_e32 v32, v43, v32
	v_mul_f32_e32 v16, 0x3db8aa3b, v16
	v_sub_f32_e32 v17, v17, v129
	v_add_f32_e32 v32, v44, v32
	v_exp_f32_e32 v16, v16
	v_mul_f32_e32 v17, 0x3db8aa3b, v17
	v_sub_f32_e32 v18, v18, v129
	v_add_f32_e32 v32, v45, v32
	v_exp_f32_e32 v17, v17
	v_mul_f32_e32 v18, 0x3db8aa3b, v18
	v_sub_f32_e32 v19, v19, v129
	v_add_f32_e32 v32, v46, v32
	v_exp_f32_e32 v18, v18
	v_mul_f32_e32 v19, 0x3db8aa3b, v19
	v_sub_f32_e32 v20, v20, v129
	v_add_f32_e32 v32, v47, v32
	v_exp_f32_e32 v19, v19
	v_mul_f32_e32 v20, 0x3db8aa3b, v20
	v_sub_f32_e32 v21, v21, v129
	v_cvt_pk_bf16_f32 v89, v34, v35
	v_cvt_pk_bf16_f32 v90, v36, v37
	v_cvt_pk_bf16_f32 v91, v38, v39
	v_cvt_pk_bf16_f32 v92, v40, v41
	v_cvt_pk_bf16_f32 v93, v42, v43
	v_cvt_pk_bf16_f32 v94, v44, v45
	v_cvt_pk_bf16_f32 v95, v46, v47
	v_exp_f32_e32 v20, v20
	v_mul_f32_e32 v21, 0x3db8aa3b, v21
	v_sub_f32_e32 v22, v22, v129
	v_cvt_pk_bf16_f32 v104, v16, v17
	v_add_f32_e32 v16, v16, v32
	v_exp_f32_e32 v21, v21
	v_mul_f32_e32 v22, 0x3db8aa3b, v22
	v_sub_f32_e32 v23, v23, v129
	v_add_f32_e32 v16, v17, v16
	v_exp_f32_e32 v22, v22
	v_mul_f32_e32 v23, 0x3db8aa3b, v23
	v_sub_f32_e32 v24, v24, v129
	v_add_f32_e32 v16, v18, v16
	v_exp_f32_e32 v23, v23
	v_mul_f32_e32 v24, 0x3db8aa3b, v24
	v_sub_f32_e32 v25, v25, v129
	v_add_f32_e32 v16, v19, v16
	v_exp_f32_e32 v24, v24
	v_mul_f32_e32 v25, 0x3db8aa3b, v25
	v_sub_f32_e32 v26, v26, v129
	v_add_f32_e32 v16, v20, v16
	v_exp_f32_e32 v25, v25
	v_mul_f32_e32 v26, 0x3db8aa3b, v26
	v_sub_f32_e32 v27, v27, v129
	v_add_f32_e32 v16, v21, v16
	v_exp_f32_e32 v26, v26
	v_mul_f32_e32 v27, 0x3db8aa3b, v27
	v_sub_f32_e32 v28, v28, v129
	v_add_f32_e32 v16, v22, v16
	v_exp_f32_e32 v27, v27
	v_mul_f32_e32 v28, 0x3db8aa3b, v28
	v_sub_f32_e32 v29, v29, v129
	v_add_f32_e32 v16, v23, v16
	v_exp_f32_e32 v28, v28
	v_mul_f32_e32 v29, 0x3db8aa3b, v29
	v_sub_f32_e32 v30, v30, v129
	v_add_f32_e32 v16, v24, v16
	v_exp_f32_e32 v29, v29
	v_mul_f32_e32 v30, 0x3db8aa3b, v30
	v_sub_f32_e32 v31, v31, v129
	v_add_f32_e32 v16, v25, v16
	v_exp_f32_e32 v30, v30
	v_mul_f32_e32 v31, 0x3db8aa3b, v31
	v_add_f32_e32 v16, v26, v16
	v_sub_f32_e32 v0, v0, v129
	v_exp_f32_e32 v31, v31
	v_add_f32_e32 v16, v27, v16
	v_mul_f32_e32 v0, 0x3db8aa3b, v0
	v_sub_f32_e32 v1, v1, v129
	v_add_f32_e32 v16, v28, v16
	v_exp_f32_e32 v0, v0
	v_mul_f32_e32 v1, 0x3db8aa3b, v1
	v_sub_f32_e32 v2, v2, v129
	v_add_f32_e32 v16, v29, v16
	v_exp_f32_e32 v1, v1
	v_mul_f32_e32 v2, 0x3db8aa3b, v2
	v_sub_f32_e32 v3, v3, v129
	v_add_f32_e32 v16, v30, v16
	v_exp_f32_e32 v2, v2
	v_mul_f32_e32 v3, 0x3db8aa3b, v3
	v_sub_f32_e32 v4, v4, v129
	v_add_f32_e32 v16, v31, v16
	v_exp_f32_e32 v3, v3
	v_mul_f32_e32 v4, 0x3db8aa3b, v4
	v_sub_f32_e32 v5, v5, v129
	v_cvt_pk_bf16_f32 v105, v18, v19
	v_cvt_pk_bf16_f32 v106, v20, v21
	v_cvt_pk_bf16_f32 v107, v22, v23
	v_cvt_pk_bf16_f32 v108, v24, v25
	v_cvt_pk_bf16_f32 v109, v26, v27
	v_cvt_pk_bf16_f32 v110, v28, v29
	v_cvt_pk_bf16_f32 v111, v30, v31
	v_exp_f32_e32 v4, v4
	v_mul_f32_e32 v5, 0x3db8aa3b, v5
	v_sub_f32_e32 v6, v6, v129
	v_cvt_pk_bf16_f32 v120, v0, v1
	v_add_f32_e32 v0, v0, v16
	v_exp_f32_e32 v5, v5
	v_mul_f32_e32 v6, 0x3db8aa3b, v6
	v_sub_f32_e32 v7, v7, v129
	v_add_f32_e32 v0, v1, v0
	v_exp_f32_e32 v6, v6
	v_mul_f32_e32 v7, 0x3db8aa3b, v7
	v_sub_f32_e32 v8, v8, v129
	v_add_f32_e32 v0, v2, v0
	v_exp_f32_e32 v7, v7
	v_mul_f32_e32 v8, 0x3db8aa3b, v8
	v_sub_f32_e32 v9, v9, v129
	v_add_f32_e32 v0, v3, v0
	v_exp_f32_e32 v8, v8
	v_mul_f32_e32 v9, 0x3db8aa3b, v9
	v_sub_f32_e32 v10, v10, v129
	v_add_f32_e32 v0, v4, v0
	v_exp_f32_e32 v9, v9
	v_mul_f32_e32 v10, 0x3db8aa3b, v10
	v_sub_f32_e32 v11, v11, v129
	v_add_f32_e32 v0, v5, v0
	v_exp_f32_e32 v10, v10
	v_mul_f32_e32 v11, 0x3db8aa3b, v11
	v_sub_f32_e32 v12, v12, v129
	v_add_f32_e32 v0, v6, v0
	v_exp_f32_e32 v11, v11
	v_mul_f32_e32 v12, 0x3db8aa3b, v12
	v_sub_f32_e32 v13, v13, v129
	v_add_f32_e32 v0, v7, v0
	v_exp_f32_e32 v12, v12
	v_mul_f32_e32 v13, 0x3db8aa3b, v13
	v_sub_f32_e32 v14, v14, v129
	v_add_f32_e32 v0, v8, v0
	v_exp_f32_e32 v13, v13
	v_mul_f32_e32 v14, 0x3db8aa3b, v14
	v_sub_f32_e32 v15, v15, v129
	v_add_f32_e32 v0, v9, v0
	v_exp_f32_e32 v14, v14
	v_mul_f32_e32 v15, 0x3db8aa3b, v15
	v_add_f32_e32 v0, v10, v0
	v_exp_f32_e32 v15, v15
	v_add_f32_e32 v0, v11, v0
	v_add_f32_e32 v0, v12, v0
	v_add_f32_e32 v0, v13, v0
	v_add_f32_e32 v0, v14, v0
	v_add_f32_e32 v26, v15, v0
	ds_bpermute_b32 v27, v128, v26
	v_lshl_add_u64 v[0:1], s[6:7], 0, v[156:157]
	s_mov_b64 s[6:7], 0x29e00000
	s_mov_b32 s0, 0
	v_lshl_add_u64 v[16:17], v[0:1], 0, s[6:7]
	s_mov_b64 s[6:7], -1
	v_cvt_pk_bf16_f32 v121, v2, v3
	v_cvt_pk_bf16_f32 v122, v4, v5
	v_cvt_pk_bf16_f32 v123, v6, v7
	v_cvt_pk_bf16_f32 v124, v8, v9
	v_cvt_pk_bf16_f32 v125, v10, v11
	v_cvt_pk_bf16_f32 v126, v12, v13
	v_cvt_pk_bf16_f32 v127, v14, v15

.LBB0_1032:
	s_mov_b64 s[0:1], s[58:59]
	s_load_dwordx2 s[10:11], s[0:1], 0x158
	s_mov_b64 s[0:1], s[58:59]
	s_mov_b64 s[12:13], s[58:59]
	s_load_dwordx2 s[16:17], s[0:1], 0x158
	s_waitcnt lgkmcnt(0)
	s_add_u32 s1, s10, 0x12f00000
	s_addc_u32 s22, s11, 0
	s_load_dwordx2 s[10:11], s[12:13], 0x90
	s_mov_b64 s[12:13], s[58:59]
	s_and_b32 s0, s8, 0xfffff800
	s_and_b32 s14, s20, 0x7c0
	s_load_dwordx2 s[12:13], s[12:13], 0x158
	v_mbcnt_lo_u32_b32 v25, -1, 0
	v_mbcnt_hi_u32_b32 v25, -1, v25
	s_or_b32 s14, s0, s14
	v_add_u32_e32 v40, s61, v25
	s_bfe_u32 s0, s56, 0x20005
	v_lshlrev_b32_e32 v11, 3, v40
	s_lshl_b32 s15, s0, 8
	v_and_b32_e32 v9, 0x78, v11
	s_add_u32 s18, s1, s15
	s_addc_u32 s19, s22, 0
	v_lshlrev_b32_e32 v156, 1, v9
	v_ashrrev_i32_e32 v24, 4, v40
	v_lshl_add_u64 v[0:1], s[18:19], 0, v[156:157]
	v_add_u32_e32 v2, s14, v24
	v_mad_i64_i32 v[4:5], s[18:19], v2, s83, v[0:1]
	v_add_co_u32_e32 v6, vcc, s72, v4
	v_add_u32_e32 v27, 0x200, v40
	s_nop 0
	v_addc_co_u32_e32 v7, vcc, 0, v5, vcc
	global_load_dwordx4 v[12:15], v[6:7], off
	v_ashrrev_i32_e32 v26, 4, v27
	s_lshl_b32 s15, s0, 9
	v_lshlrev_b32_e32 v2, 2, v9
	v_add_u32_e32 v3, s14, v26
	s_add_i32 s15, s15, 0
	v_add_u32_e32 v10, s43, v2
	v_mad_i64_i32 v[0:1], s[18:19], v3, s83, v[0:1]
	v_add_u32_e32 v2, s15, v2
	v_add_u32_e32 v50, 0x22400, v2
	v_add_co_u32_e32 v42, vcc, s72, v0
	ds_read_b128 v[16:19], v50
	s_nop 0
	v_addc_co_u32_e32 v43, vcc, 0, v1, vcc
	global_load_dwordx4 v[0:3], v[0:1], off offset:3072
	s_nop 0
	global_load_dwordx4 v[20:23], v[6:7], off offset:1024
	global_load_dwordx4 v[70:73], v[6:7], off offset:2048 nt
	global_load_dwordx4 v[74:77], v[42:43], off offset:2048 nt
	global_load_dwordx4 v[102:105], v[42:43], off offset:1024 nt
	v_lshlrev_b32_e32 v78, 9, v24
	v_lshlrev_b32_e32 v79, 4, v40
	v_and_b32_e32 v79, 0xf0, v79
	v_or_b32_e32 v78, v78, v79
	v_mov_b32_e32 v79, 0
	v_lshl_add_u64 v[78:79], s[16:17], 0, v[78:79]
	v_lshl_add_u64 v[78:79], v[78:79], 0, s[4:5]
	v_mov_b32_e32 v80, 0x4000
	v_mov_b32_e32 v81, 0
	v_lshl_add_u64 v[80:81], v[78:79], 0, v[80:81]
	global_load_dwordx4 v[82:85], v[78:79], off nt
	global_load_dwordx4 v[86:89], v[78:79], off offset:256 nt
	global_load_dwordx4 v[94:97], v[80:81], off nt
	global_load_dwordx4 v[98:101], v[80:81], off offset:256 nt
	s_nop 0
	global_load_dwordx4 v[4:7], v[4:5], off offset:3072
	ds_read_b128 v[28:31], v50 offset:16
	global_load_dwordx4 v[32:35], v[42:43], off
	s_waitcnt lgkmcnt(0)
	v_mov_b32_e32 v37, v18
	v_mov_b32_e32 v18, v17
	v_mov_b32_e32 v36, v16
	v_mov_b32_e32 v16, v28
	v_pk_add_f32 v[44:45], v[18:19], 1.0 op_sel_hi:[1,0] neg_lo:[1,0] neg_hi:[1,0]
	v_pk_add_f32 v[38:39], v[36:37], 1.0 op_sel_hi:[1,0] neg_lo:[1,0] neg_hi:[1,0]
	v_mul_u32_u24_e32 v52, 0x90, v9
	s_waitcnt vmcnt(0)
	v_lshlrev_b32_e32 v8, 16, v12
	v_and_b32_e32 v12, 0xffff0000, v12
	v_lshlrev_b32_e32 v17, 16, v13
	v_and_b32_e32 v13, 0xffff0000, v13
	v_lshlrev_b32_e32 v28, 16, v14
	v_and_b32_e32 v14, 0xffff0000, v14
	v_lshlrev_b32_e32 v41, 16, v15
	v_and_b32_e32 v15, 0xffff0000, v15
	v_mul_f32_e32 v12, 0xbfb8aa3b, v12
	v_mul_f32_e32 v13, 0xbfb8aa3b, v13
	v_mul_f32_e32 v8, 0xbfb8aa3b, v8
	v_mul_f32_e32 v17, 0xbfb8aa3b, v17
	v_mul_f32_e32 v28, 0xbfb8aa3b, v28
	v_mul_f32_e32 v14, 0xbfb8aa3b, v14
	v_mul_f32_e32 v41, 0xbfb8aa3b, v41
	v_mul_f32_e32 v15, 0xbfb8aa3b, v15
	v_exp_f32_e32 v12, v12
	v_exp_f32_e32 v13, v13
	v_exp_f32_e32 v8, v8
	v_exp_f32_e32 v17, v17
	v_exp_f32_e32 v28, v28
	v_exp_f32_e32 v14, v14
	v_exp_f32_e32 v41, v41
	v_exp_f32_e32 v15, v15
	v_add_f32_e32 v46, 1.0, v12
	v_add_f32_e32 v47, 1.0, v13
	v_add_f32_e32 v8, 1.0, v8
	v_add_f32_e32 v17, 1.0, v17
	v_add_f32_e32 v28, 1.0, v28
	v_add_f32_e32 v48, 1.0, v14
	v_add_f32_e32 v41, 1.0, v41
	v_add_f32_e32 v49, 1.0, v15
	v_rcp_f32_e32 v14, v46
	v_rcp_f32_e32 v15, v47
	v_rcp_f32_e32 v12, v8
	v_rcp_f32_e32 v13, v17
	v_rcp_f32_e32 v46, v28
	v_rcp_f32_e32 v47, v41
	v_rcp_f32_e32 v48, v48
	v_rcp_f32_e32 v49, v49
	v_mov_b32_e32 v17, v30
	v_pk_fma_f32 v[14:15], v[14:15], v[44:45], v[18:19]
	v_pk_add_f32 v[18:19], v[16:17], 1.0 op_sel_hi:[1,0] neg_lo:[1,0] neg_hi:[1,0]
	v_mov_b32_e32 v30, v29
	v_pk_fma_f32 v[12:13], v[12:13], v[38:39], v[36:37]
	v_pk_fma_f32 v[16:17], v[46:47], v[18:19], v[16:17]
	v_pk_add_f32 v[18:19], v[30:31], 1.0 op_sel_hi:[1,0] neg_lo:[1,0] neg_hi:[1,0]
	v_log_f32_e32 v36, v12
	v_log_f32_e32 v37, v14
	v_log_f32_e32 v38, v13
	v_log_f32_e32 v39, v15
	v_pk_fma_f32 v[18:19], v[48:49], v[18:19], v[30:31]
	v_log_f32_e32 v44, v16
	v_log_f32_e32 v46, v17
	v_log_f32_e32 v47, v19
	v_log_f32_e32 v45, v18
	v_lshlrev_b32_e32 v8, 9, v24
	v_pk_mul_f32 v[30:31], v[38:39], s[70:71] op_sel_hi:[1,0]
	v_pk_mul_f32 v[28:29], v[36:37], s[70:71] op_sel_hi:[1,0]
	v_add_u32_e32 v41, v10, v8
	v_bitop3_b32 v8, v24, 56, v11 bitop3:0x48
	v_pk_mul_f32 v[38:39], v[46:47], s[70:71] op_sel_hi:[1,0]
	v_pk_mul_f32 v[36:37], v[44:45], s[70:71] op_sel_hi:[1,0]
	ds_write_b128 v41, v[28:31]
	ds_write_b128 v41, v[36:39] offset:16
	v_lshl_add_u32 v28, v8, 1, 0
	v_lshlrev_b32_e32 v8, 1, v24
	v_and_b32_e32 v29, 14, v8
	v_add3_u32 v28, v28, v29, v52
	ds_write_b16 v28, v20 offset:44032
	ds_write_b16_d16_hi v28, v20 offset:44176
	ds_write_b16 v28, v21 offset:44320
	ds_write_b16_d16_hi v28, v21 offset:44464
	ds_write_b16 v28, v22 offset:44608
	ds_write_b16_d16_hi v28, v22 offset:44752
	v_mov_b32_e32 v36, v102
	v_mov_b32_e32 v37, v103
	v_mov_b32_e32 v38, v104
	v_mov_b32_e32 v39, v105
	v_and_b32_e32 v21, 0xffff0000, v32
	v_lshlrev_b32_e32 v20, 16, v32
	v_lshlrev_b32_e32 v22, 16, v33
	v_mul_f32_e32 v21, 0xbfb8aa3b, v21
	ds_write_b16 v28, v23 offset:44896
	ds_write_b16_d16_hi v28, v23 offset:45040
	v_and_b32_e32 v23, 0xffff0000, v33
	v_mul_f32_e32 v20, 0xbfb8aa3b, v20
	v_exp_f32_e32 v21, v21
	v_mul_f32_e32 v22, 0xbfb8aa3b, v22
	v_exp_f32_e32 v20, v20
	v_exp_f32_e32 v32, v22
	v_mul_f32_e32 v22, 0xbfb8aa3b, v23
	v_exp_f32_e32 v23, v22
	ds_read_b128 v[28:31], v50
	ds_read_b128 v[42:45], v50 offset:16
	v_add_f32_e32 v21, 1.0, v21
	v_add_f32_e32 v20, 1.0, v20
	v_rcp_f32_e32 v22, v21
	v_add_f32_e32 v21, 1.0, v32
	v_rcp_f32_e32 v20, v20
	v_rcp_f32_e32 v21, v21
	v_add_f32_e32 v23, 1.0, v23
	v_rcp_f32_e32 v23, v23
	s_waitcnt lgkmcnt(1)
	v_mov_b32_e32 v32, v28
	v_mov_b32_e32 v33, v30
	v_lshlrev_b32_e32 v46, 16, v34
	v_and_b32_e32 v47, 0xffff0000, v34
	v_lshlrev_b32_e32 v48, 16, v35
	v_and_b32_e32 v49, 0xffff0000, v35
	v_pk_add_f32 v[34:35], v[32:33], 1.0 op_sel_hi:[1,0] neg_lo:[1,0] neg_hi:[1,0]
	v_mov_b32_e32 v30, v29
	v_pk_fma_f32 v[20:21], v[20:21], v[34:35], v[32:33]
	v_pk_add_f32 v[32:33], v[30:31], 1.0 op_sel_hi:[1,0] neg_lo:[1,0] neg_hi:[1,0]
	v_log_f32_e32 v28, v20
	v_pk_fma_f32 v[22:23], v[22:23], v[32:33], v[30:31]
	v_mul_f32_e32 v31, 0xbfb8aa3b, v47
	v_mul_f32_e32 v30, 0xbfb8aa3b, v46
	v_exp_f32_e32 v31, v31
	v_mul_f32_e32 v32, 0xbfb8aa3b, v48
	v_exp_f32_e32 v30, v30
	v_exp_f32_e32 v32, v32
	v_mul_f32_e32 v33, 0xbfb8aa3b, v49
	v_exp_f32_e32 v33, v33
	v_add_f32_e32 v31, 1.0, v31
	v_add_f32_e32 v30, 1.0, v30
	v_rcp_f32_e32 v46, v31
	v_add_f32_e32 v31, 1.0, v32
	v_rcp_f32_e32 v30, v30
	v_rcp_f32_e32 v31, v31
	v_add_f32_e32 v32, 1.0, v33
	v_rcp_f32_e32 v47, v32
	s_waitcnt lgkmcnt(0)
	v_mov_b32_e32 v32, v42
	v_mov_b32_e32 v33, v44
	v_pk_add_f32 v[48:49], v[32:33], 1.0 op_sel_hi:[1,0] neg_lo:[1,0] neg_hi:[1,0]
	v_mov_b32_e32 v44, v43
	v_pk_fma_f32 v[32:33], v[30:31], v[48:49], v[32:33]
	v_pk_add_f32 v[30:31], v[44:45], 1.0 op_sel_hi:[1,0] neg_lo:[1,0] neg_hi:[1,0]
	v_log_f32_e32 v29, v22
	v_pk_fma_f32 v[30:31], v[46:47], v[30:31], v[44:45]
	v_log_f32_e32 v42, v32
	v_log_f32_e32 v48, v33
	v_log_f32_e32 v49, v31
	v_log_f32_e32 v43, v30
	v_log_f32_e32 v34, v21
	v_log_f32_e32 v35, v23
	v_pk_mul_f32 v[44:45], v[28:29], s[70:71] op_sel_hi:[1,0]
	v_lshlrev_b32_e32 v28, 9, v26
	v_pk_mul_f32 v[50:51], v[48:49], s[70:71] op_sel_hi:[1,0]
	v_pk_mul_f32 v[48:49], v[42:43], s[70:71] op_sel_hi:[1,0]
	v_add_u32_e32 v42, v10, v28
	v_bitop3_b32 v10, v26, 56, v11 bitop3:0x48
	v_lshl_add_u32 v28, v10, 1, 0
	v_lshlrev_b32_e32 v10, 1, v26
	v_and_b32_e32 v29, 14, v10
	v_pk_mul_f32 v[46:47], v[34:35], s[70:71] op_sel_hi:[1,0]
	v_add3_u32 v28, v28, v29, v52
	ds_write_b128 v42, v[44:47]
	ds_write_b128 v42, v[48:51] offset:16
	s_waitcnt vmcnt(0)
	ds_write_b16 v28, v36 offset:44032
	ds_write_b16_d16_hi v28, v36 offset:44176
	ds_write_b16 v28, v37 offset:44320
	ds_write_b16_d16_hi v28, v37 offset:44464
	ds_write_b16 v28, v38 offset:44608
	ds_write_b16_d16_hi v28, v38 offset:44752
	ds_write_b16 v28, v39 offset:44896
	ds_write_b16_d16_hi v28, v39 offset:45040
	v_and_b32_e32 v29, 0x7f, v40
	v_ashrrev_i32_e32 v28, 7, v40
	v_lshlrev_b32_e32 v34, 13, v28
	v_lshlrev_b32_e32 v29, 2, v29
	v_add3_u32 v43, s43, v34, v29
	s_waitcnt lgkmcnt(0)
	s_barrier
	ds_read2st64_b32 v[34:35], v43 offset1:2
	ds_read2st64_b32 v[36:37], v43 offset0:4 offset1:6
	ds_read2st64_b32 v[38:39], v43 offset0:8 offset1:10
	v_mov_b32_e32 v44, 0
	v_add_u32_e32 v29, 0, v29
	s_waitcnt lgkmcnt(2)
	v_add_f32_e32 v45, 0, v34
	v_add_f32_e32 v47, v45, v35
	ds_read2st64_b32 v[34:35], v43 offset0:12 offset1:14
	s_waitcnt lgkmcnt(2)
	v_add_f32_e32 v46, v47, v36
	v_add_f32_e32 v49, v46, v37
	s_waitcnt lgkmcnt(1)
	v_add_f32_e32 v48, v49, v38
	ds_read2st64_b32 v[36:37], v43 offset0:16 offset1:18
	v_add_f32_e32 v52, v48, v39
	s_waitcnt lgkmcnt(1)
	v_add_f32_e32 v50, v52, v34
	v_add_f32_e32 v51, v50, v35
	ds_read2st64_b32 v[34:35], v43 offset0:20 offset1:22
	ds_read2st64_b32 v[38:39], v43 offset0:24 offset1:26
	s_waitcnt lgkmcnt(2)
	v_add_f32_e32 v53, v51, v36
	v_add_f32_e32 v54, v53, v37
	ds_read2st64_b32 v[36:37], v43 offset0:28 offset1:30
	s_waitcnt lgkmcnt(2)
	v_add_f32_e32 v59, v54, v34
	v_add_f32_e32 v60, v59, v35
	s_waitcnt lgkmcnt(1)
	v_add_f32_e32 v57, v60, v38
	v_add_f32_e32 v58, v57, v39
	s_waitcnt lgkmcnt(0)
	v_add_f32_e32 v55, v58, v36
	v_add_f32_e32 v56, v55, v37
	v_lshl_add_u32 v34, v40, 2, 0
	v_cmp_lt_i32_e32 vcc, 0, v28
	ds_write_b32 v34, v56 offset:62464
	s_waitcnt lgkmcnt(0)
	s_barrier
	s_and_saveexec_b64 s[18:19], vcc
	s_cbranch_execz .LBB0_1040
	ds_read_b32 v34, v29 offset:62464
	s_waitcnt lgkmcnt(0)
	v_add_f32_e32 v44, 0, v34
	s_or_b64 exec, exec, s[18:19]
	v_cmp_lt_i32_e32 vcc, 1, v28
	s_and_saveexec_b64 s[18:19], vcc
	s_cbranch_execnz .LBB0_1041
